# p8 LN1: gain/bias vectors loaded once per phase instead of four load+wait pairs per token
# speedup vs baseline: 1.0026x; 1.0026x over previous
; DEVI char* wsp(const Params& P, size_t off) { asm volatile("" : "+s"(off)); return P.ws + off; }
; DEVI int ltid() { int t = threadIdx.x; asm volatile("" : "+v"(t)); return t; }
; DEVI void phase8(const Params& P, int l, int pass) {
;   const int tid = ltid();
;   const int ntok = pass ? 8192 : 8448, base = pass ? 8448 : 0;
;   const int w = tid >> 6, lane = tid & 63;
;   const float* pre = (const float*)wsp(P, O_PRE);
;   const float* g = P.in[22] + l * 1024;
;   const float* b = P.in[23] + l * 1024;
;   bfu* xb = (bfu*)wsp(P, O_XB);
;   for (int id = blockIdx.x; id < ntok / 4; id += gridDim.x) {
;     int lt = id * 4 + w, it = base + lt;
;     const float* src = pre + (long)lt * 1024;
.LBB0_892:
	s_or_b64 exec, exec, s[26:27]
	s_barrier
	s_cmp_eq_u32 s90, 0
	s_cselect_b64 s[42:43], -1, 0
	s_and_b64 s[44:45], s[42:43], exec
	s_movk_i32 s1, 0x840
	s_cselect_b32 s1, s1, 0x800
	v_mov_b32_e32 v0, v93
	s_mov_b64 s[26:27], 0x8582000
	s_mov_b64 s[40:41], 0x6502000
	s_cmp_ge_i32 s74, s1
	s_cbranch_scc1 .LBB0_903
	v_and_b32_e32 v2, 64, v187
	v_add_u32_e32 v2, 64, v2
	v_xor_b32_e32 v3, 32, v187
	v_cmp_lt_i32_e32 vcc, v3, v2
	s_and_b64 s[42:43], s[42:43], exec
	s_cselect_b32 s2, 0, 0x2100
	v_cndmask_b32_e32 v3, v187, v3, vcc
	v_lshlrev_b32_e32 v28, 2, v3
	v_xor_b32_e32 v3, 16, v187
	v_cmp_lt_i32_e32 vcc, v3, v2
	s_add_u32 s40, s30, s40
	s_addc_u32 s41, s31, s41
	v_cndmask_b32_e32 v3, v187, v3, vcc
	v_lshlrev_b32_e32 v29, 2, v3
	v_xor_b32_e32 v3, 8, v187
	v_cmp_lt_i32_e32 vcc, v3, v2
	s_lshl_b32 s42, s0, 10
	s_ashr_i32 s43, s42, 31
	v_cndmask_b32_e32 v3, v187, v3, vcc
	v_lshlrev_b32_e32 v30, 2, v3
	v_xor_b32_e32 v3, 4, v187
	v_readlane_b32 s4, v253, 14
	v_cmp_lt_i32_e32 vcc, v3, v2
	s_lshl_b64 s[42:43], s[42:43], 2
	v_readlane_b32 s6, v253, 16
	v_cndmask_b32_e32 v3, v187, v3, vcc
	v_readlane_b32 s7, v253, 17
	s_add_u32 s44, s6, s42
	v_lshlrev_b32_e32 v31, 2, v3
	v_xor_b32_e32 v3, 2, v187
	s_addc_u32 s45, s7, s43
	v_cmp_lt_i32_e32 vcc, v3, v2
	v_readlane_b32 s5, v253, 15
	s_add_u32 s42, s4, s42
	v_cndmask_b32_e32 v3, v187, v3, vcc
	v_ashrrev_i32_e32 v8, 6, v0
	s_addc_u32 s43, s5, s43
	v_lshlrev_b32_e32 v0, 2, v0
	v_lshlrev_b32_e32 v32, 2, v3
	v_xor_b32_e32 v3, 1, v187
	s_add_u32 s26, s30, s26
	v_and_b32_e32 v10, 0xfc, v0
	v_cmp_lt_i32_e32 vcc, v3, v2
	s_addc_u32 s27, s31, s27
	v_lshlrev_b32_e32 v88, 2, v10
	v_cndmask_b32_e32 v2, v187, v3, vcc
	v_lshl_add_u64 v[0:1], s[26:27], 0, v[88:89]
	v_lshlrev_b32_e32 v33, 2, v2
	v_lshl_add_u64 v[2:3], s[42:43], 0, v[88:89]
	v_lshl_add_u64 v[4:5], s[44:45], 0, v[88:89]
	v_lshlrev_b32_e32 v88, 1, v10
	v_readlane_b32 s4, v252, 24
	v_readlane_b32 s23, v252, 31
	v_lshl_add_u64 v[6:7], s[40:41], 0, v[88:89]
	v_add_u32_e32 v8, s4, v8
	v_lshlrev_b32_e32 v88, 2, v10
	s_mov_b32 s24, s74
	v_readlane_b32 s8, v253, 18
	v_readlane_b32 s9, v253, 19
	v_readlane_b32 s10, v253, 20
	v_readlane_b32 s11, v253, 21
	v_readlane_b32 s12, v253, 22
	v_readlane_b32 s13, v253, 23
	v_readlane_b32 s14, v253, 24
	v_readlane_b32 s15, v253, 25
	v_readlane_b32 s16, v253, 26
	v_readlane_b32 s17, v253, 27
	v_readlane_b32 s18, v253, 28
	v_readlane_b32 s19, v253, 29
	global_load_dwordx4 v[208:211], v[2:3], off
	global_load_dwordx4 v[224:227], v[4:5], off
	global_load_dwordx4 v[212:215], v[2:3], off offset:1024
	global_load_dwordx4 v[228:231], v[4:5], off offset:1024
	global_load_dwordx4 v[216:219], v[2:3], off offset:2048
	global_load_dwordx4 v[232:235], v[4:5], off offset:2048
	global_load_dwordx4 v[220:223], v[2:3], off offset:3072
	global_load_dwordx4 v[236:239], v[4:5], off offset:3072
	s_branch .LBB0_895
; DEVI void phase8(const Params& P, int l, int pass) {
;     ...
;     float rs = rsqrtf(wave_sum(ss) * (1.f / 1024.f) + 1e-5f);
;     float* xr = xrow(P, it);
; #pragma unroll
;     for (int q = 0; q < 4; ++q) {
;       int c = q * 256 + lane * 4;
;       float o[4];
; #pragma unroll
;       for (int i = 0; i < 4; ++i) o[i] = (v[q * 4 + i] - mu) * rs * g[c + i] + b[c + i];
;       *reinterpret_cast<float4*>(xr + c) = make_float4(o[0], o[1], o[2], o[3]);
;       store4bf(xb + (long)it * 1024 + c, o);
;     }
.LBB0_894:
	s_or_b64 exec, exec, s[40:41]
	v_mov_b32_e32 v36, v208
	v_mov_b32_e32 v37, v209
	v_mov_b32_e32 v38, v210
	v_mov_b32_e32 v39, v211
	v_mov_b32_e32 v40, v224
	v_mov_b32_e32 v41, v225
	v_mov_b32_e32 v42, v226
	v_mov_b32_e32 v43, v227
	s_waitcnt lgkmcnt(0)
	v_add_f32_e32 v9, v9, v27
	v_lshl_or_b32 v44, v34, 12, v35
	v_lshl_add_u32 v34, v34, 5, v35
	v_mov_b32_e32 v46, s33
	v_mov_b32_e32 v47, s28
	v_fmamk_f32 v9, v9, 0x3a800000, v184
	v_cndmask_b32_e64 v34, v34, v44, s[26:27]
	v_cndmask_b32_e64 v44, v46, v47, s[26:27]
	v_mul_f32_e32 v46, 0x4b800000, v9
	v_cmp_gt_f32_e32 vcc, s34, v9
	v_mov_b32_e32 v35, s93
	v_mov_b32_e32 v45, s29
	v_cndmask_b32_e32 v9, v9, v46, vcc
	v_rsq_f32_e32 v9, v9
	v_cndmask_b32_e64 v45, v35, v45, s[26:27]
	v_ashrrev_i32_e32 v35, 31, v34
	v_lshlrev_b64 v[34:35], 12, v[34:35]
	v_lshl_add_u64 v[34:35], v[44:45], 0, v[34:35]
	v_lshl_add_u64 v[44:45], v[34:35], 0, v[88:89]
	v_mul_f32_e32 v34, 0x45800000, v9
	v_cndmask_b32_e32 v46, v9, v34, vcc
	v_pk_mul_f32 v[22:23], v[22:23], v[46:47] op_sel_hi:[1,0]
	v_pk_mul_f32 v[24:25], v[24:25], v[46:47] op_sel_hi:[1,0]
	v_ashrrev_i32_e32 v27, 31, v26
	v_lshlrev_b64 v[26:27], 11, v[26:27]
	v_lshl_add_u64 v[26:27], v[6:7], 0, v[26:27]
	v_pk_mul_f32 v[18:19], v[18:19], v[46:47] op_sel_hi:[1,0]
	v_pk_mul_f32 v[20:21], v[20:21], v[46:47] op_sel_hi:[1,0]
	v_pk_mul_f32 v[14:15], v[14:15], v[46:47] op_sel_hi:[1,0]
	v_pk_mul_f32 v[16:17], v[16:17], v[46:47] op_sel_hi:[1,0]
	v_pk_mul_f32 v[10:11], v[10:11], v[46:47] op_sel_hi:[1,0]
	v_pk_mul_f32 v[12:13], v[12:13], v[46:47] op_sel_hi:[1,0]
	s_add_i32 s24, s24, s23
	s_cmp_lt_i32 s24, s1
	v_add_u32_e32 v8, s72, v8
	v_pk_fma_f32 v[22:23], v[22:23], v[36:37], v[40:41]
	v_pk_fma_f32 v[24:25], v[24:25], v[38:39], v[42:43]
	v_and_b32_sdwa v36, v23, v95 dst_sel:DWORD dst_unused:UNUSED_PAD src0_sel:WORD_1 src1_sel:DWORD
	v_and_b32_sdwa v9, v24, v95 dst_sel:DWORD dst_unused:UNUSED_PAD src0_sel:WORD_1 src1_sel:DWORD
	v_and_b32_sdwa v35, v25, v95 dst_sel:DWORD dst_unused:UNUSED_PAD src0_sel:WORD_1 src1_sel:DWORD
	global_store_dwordx4 v[44:45], v[22:25], off
	v_and_b32_sdwa v34, v22, v95 dst_sel:DWORD dst_unused:UNUSED_PAD src0_sel:WORD_1 src1_sel:DWORD
	v_add3_u32 v9, v24, v9, s39
	v_add3_u32 v24, v25, v35, s39
	v_add3_u32 v23, v23, v36, s39
	v_add3_u32 v22, v22, v34, s39
	v_and_b32_e32 v24, 0xffff0000, v24
	v_and_b32_e32 v25, 0xffff0000, v23
	v_or_b32_sdwa v23, v24, v9 dst_sel:DWORD dst_unused:UNUSED_PAD src0_sel:DWORD src1_sel:WORD_1
	v_or_b32_sdwa v22, v25, v22 dst_sel:DWORD dst_unused:UNUSED_PAD src0_sel:DWORD src1_sel:WORD_1
	global_store_dwordx2 v[26:27], v[22:23], off
	v_mov_b32_e32 v22, v212
	v_mov_b32_e32 v23, v213
	v_mov_b32_e32 v24, v214
	v_mov_b32_e32 v25, v215
	s_nop 0
	v_mov_b32_e32 v34, v228
	v_mov_b32_e32 v35, v229
	v_mov_b32_e32 v36, v230
	v_mov_b32_e32 v37, v231
	v_pk_fma_f32 v[18:19], v[18:19], v[22:23], v[34:35]
	v_pk_fma_f32 v[20:21], v[20:21], v[24:25], v[36:37]
	v_and_b32_sdwa v24, v19, v95 dst_sel:DWORD dst_unused:UNUSED_PAD src0_sel:WORD_1 src1_sel:DWORD
	v_and_b32_sdwa v9, v20, v95 dst_sel:DWORD dst_unused:UNUSED_PAD src0_sel:WORD_1 src1_sel:DWORD
	v_and_b32_sdwa v23, v21, v95 dst_sel:DWORD dst_unused:UNUSED_PAD src0_sel:WORD_1 src1_sel:DWORD
	global_store_dwordx4 v[44:45], v[18:21], off offset:1024
	v_and_b32_sdwa v22, v18, v95 dst_sel:DWORD dst_unused:UNUSED_PAD src0_sel:WORD_1 src1_sel:DWORD
	v_add3_u32 v9, v20, v9, s39
	v_add3_u32 v20, v21, v23, s39
	v_add3_u32 v19, v19, v24, s39
	v_add3_u32 v18, v18, v22, s39
	v_and_b32_e32 v20, 0xffff0000, v20
	v_and_b32_e32 v21, 0xffff0000, v19
	v_or_b32_sdwa v19, v20, v9 dst_sel:DWORD dst_unused:UNUSED_PAD src0_sel:DWORD src1_sel:WORD_1
	v_or_b32_sdwa v18, v21, v18 dst_sel:DWORD dst_unused:UNUSED_PAD src0_sel:DWORD src1_sel:WORD_1
	global_store_dwordx2 v[26:27], v[18:19], off offset:512
	v_mov_b32_e32 v18, v216
	v_mov_b32_e32 v19, v217
	v_mov_b32_e32 v20, v218
	v_mov_b32_e32 v21, v219
	s_nop 0
	v_mov_b32_e32 v22, v232
	v_mov_b32_e32 v23, v233
	v_mov_b32_e32 v24, v234
	v_mov_b32_e32 v25, v235
	v_pk_fma_f32 v[14:15], v[14:15], v[18:19], v[22:23]
	v_pk_fma_f32 v[16:17], v[16:17], v[20:21], v[24:25]
	v_and_b32_sdwa v20, v15, v95 dst_sel:DWORD dst_unused:UNUSED_PAD src0_sel:WORD_1 src1_sel:DWORD
	v_and_b32_sdwa v9, v16, v95 dst_sel:DWORD dst_unused:UNUSED_PAD src0_sel:WORD_1 src1_sel:DWORD
	v_and_b32_sdwa v19, v17, v95 dst_sel:DWORD dst_unused:UNUSED_PAD src0_sel:WORD_1 src1_sel:DWORD
	global_store_dwordx4 v[44:45], v[14:17], off offset:2048
	v_and_b32_sdwa v18, v14, v95 dst_sel:DWORD dst_unused:UNUSED_PAD src0_sel:WORD_1 src1_sel:DWORD
	v_add3_u32 v9, v16, v9, s39
	v_add3_u32 v16, v17, v19, s39
	v_add3_u32 v15, v15, v20, s39
	v_add3_u32 v14, v14, v18, s39
	v_and_b32_e32 v16, 0xffff0000, v16
	v_and_b32_e32 v17, 0xffff0000, v15
	v_or_b32_sdwa v15, v16, v9 dst_sel:DWORD dst_unused:UNUSED_PAD src0_sel:DWORD src1_sel:WORD_1
	v_or_b32_sdwa v14, v17, v14 dst_sel:DWORD dst_unused:UNUSED_PAD src0_sel:DWORD src1_sel:WORD_1
	global_store_dwordx2 v[26:27], v[14:15], off offset:1024
	v_mov_b32_e32 v14, v220
	v_mov_b32_e32 v15, v221
	v_mov_b32_e32 v16, v222
	v_mov_b32_e32 v17, v223
	s_nop 0
	v_mov_b32_e32 v18, v236
	v_mov_b32_e32 v19, v237
	v_mov_b32_e32 v20, v238
	v_mov_b32_e32 v21, v239
	v_pk_fma_f32 v[10:11], v[10:11], v[14:15], v[18:19]
	v_pk_fma_f32 v[12:13], v[12:13], v[16:17], v[20:21]
	v_and_b32_sdwa v16, v11, v95 dst_sel:DWORD dst_unused:UNUSED_PAD src0_sel:WORD_1 src1_sel:DWORD
	v_and_b32_sdwa v9, v12, v95 dst_sel:DWORD dst_unused:UNUSED_PAD src0_sel:WORD_1 src1_sel:DWORD
	v_and_b32_sdwa v15, v13, v95 dst_sel:DWORD dst_unused:UNUSED_PAD src0_sel:WORD_1 src1_sel:DWORD
	global_store_dwordx4 v[44:45], v[10:13], off offset:3072
	v_and_b32_sdwa v14, v10, v95 dst_sel:DWORD dst_unused:UNUSED_PAD src0_sel:WORD_1 src1_sel:DWORD
	v_add3_u32 v9, v12, v9, s39
	v_add3_u32 v12, v13, v15, s39
	v_add3_u32 v11, v11, v16, s39
	v_add3_u32 v10, v10, v14, s39
	v_and_b32_e32 v12, 0xffff0000, v12
	v_and_b32_e32 v13, 0xffff0000, v11
	v_or_b32_sdwa v11, v12, v9 dst_sel:DWORD dst_unused:UNUSED_PAD src0_sel:DWORD src1_sel:WORD_1
	v_or_b32_sdwa v10, v13, v10 dst_sel:DWORD dst_unused:UNUSED_PAD src0_sel:DWORD src1_sel:WORD_1
	global_store_dwordx2 v[26:27], v[10:11], off offset:1536
	s_cbranch_scc0 .LBB0_903
